# v_comb1 + flat hand-written grid barrier protocol (per-instance generation constants, global-last leader releases all XCD generation words)
# speedup vs baseline: 1.0132x; 1.0053x over previous
.LBB0_124:
	s_or_b64 exec, exec, s[4:5]
	s_waitcnt vmcnt(0)
	s_barrier
	s_mov_b64 s[4:5], exec
	v_readlane_b32 s0, v219, 25
	v_readlane_b32 s1, v219, 26
	s_and_b64 s[0:1], s[4:5], s[0:1]
	s_mov_b64 exec, s[0:1]
	s_cbranch_execz .LBB0_176
	v_readlane_b32 s0, v219, 27
	v_readlane_b32 s1, v219, 28
	v_readlane_b32 s2, v219, 29
	v_mov_b32_e32 v0, 0x24000
	s_waitcnt vmcnt(0) lgkmcnt(0)
	ds_read_b32 v2, v0
	ds_read_b32 v0, v0 offset:4
	s_lshl_b32 s3, s2, 8
	s_add_i32 s14, s3, 0x2400
	s_add_i32 s3, s3, 0x1400
	v_mov_b32_e32 v1, s3
	s_waitcnt lgkmcnt(0)
	v_readfirstlane_b32 s10, v2
	v_readfirstlane_b32 s11, v0
	v_mov_b32_e32 v0, 1
	s_nop 1
	global_atomic_add v2, v1, v0, s[0:1] sc0
	s_mul_i32 s10, s10, 2
	s_mul_i32 s11, s11, 2
	s_waitcnt vmcnt(0)
	v_readfirstlane_b32 s13, v2
	s_nop 1
	s_add_i32 s13, s13, 1
	s_cmp_lg_u32 s13, s10
	s_cbranch_scc1 .Lnb2_wait
	buffer_wbl2 sc1
	s_waitcnt vmcnt(0)
	v_mov_b32_e32 v1, 0x3400
	global_atomic_add v2, v1, v0, s[0:1] sc0
	s_waitcnt vmcnt(0)
	v_readfirstlane_b32 s13, v2
	s_nop 1
	s_add_i32 s13, s13, 1
	s_cmp_lg_u32 s13, s11
	s_cbranch_scc1 .Lnb2_wait
	v_mov_b32_e32 v1, 0x2400
	global_atomic_add v1, v0, s[0:1]
	global_atomic_add v1, v0, s[0:1] offset:256
	global_atomic_add v1, v0, s[0:1] offset:512
	global_atomic_add v1, v0, s[0:1] offset:768
	global_atomic_add v1, v0, s[0:1] offset:1024
	global_atomic_add v1, v0, s[0:1] offset:1280
	global_atomic_add v1, v0, s[0:1] offset:1536
	global_atomic_add v1, v0, s[0:1] offset:1792
	global_atomic_add v1, v0, s[0:1] offset:2048
	global_atomic_add v1, v0, s[0:1] offset:2304
	global_atomic_add v1, v0, s[0:1] offset:2560
	global_atomic_add v1, v0, s[0:1] offset:2816
	global_atomic_add v1, v0, s[0:1] offset:3072
	global_atomic_add v1, v0, s[0:1] offset:3328
	global_atomic_add v1, v0, s[0:1] offset:3584
	global_atomic_add v1, v0, s[0:1] offset:3840
	v_mov_b32_e32 v1, 0x3500
	global_atomic_add v1, v0, s[0:1]
.Lnb2_wait:
	v_mov_b32_e32 v1, s14
	s_mov_b32 s15, 0
.Lnb2_spin:
	global_load_dword v2, v1, s[0:1] sc1
	s_waitcnt vmcnt(0)
	v_readfirstlane_b32 s13, v2
	s_nop 1
	s_cmp_ge_u32 s13, 2
	s_cbranch_scc1 .Lnb2_done
	s_sleep 1
	s_add_i32 s15, s15, 1
	s_cmp_lt_u32 s15, 0x200000
	s_cbranch_scc1 .Lnb2_spin
.Lnb2_done:
	buffer_inv sc1
	s_waitcnt vmcnt(0)

.LBB0_274:
	s_waitcnt vmcnt(0)
	s_waitcnt vmcnt(0) lgkmcnt(0)
	s_barrier
	s_mov_b64 s[4:5], exec
	v_readlane_b32 s0, v219, 25
	v_readlane_b32 s1, v219, 26
	s_and_b64 s[0:1], s[4:5], s[0:1]
	s_mov_b64 exec, s[0:1]
	s_cbranch_execz .LBB0_326
	v_readlane_b32 s0, v219, 27
	v_readlane_b32 s1, v219, 28
	v_readlane_b32 s2, v219, 29
	v_mov_b32_e32 v0, 0x24000
	s_waitcnt vmcnt(0) lgkmcnt(0)
	ds_read_b32 v2, v0
	ds_read_b32 v0, v0 offset:4
	s_lshl_b32 s3, s2, 8
	s_add_i32 s14, s3, 0x2400
	s_add_i32 s3, s3, 0x1400
	v_mov_b32_e32 v1, s3
	s_waitcnt lgkmcnt(0)
	v_readfirstlane_b32 s10, v2
	v_readfirstlane_b32 s11, v0
	v_mov_b32_e32 v0, 1
	s_nop 1
	global_atomic_add v2, v1, v0, s[0:1] sc0
	s_mul_i32 s10, s10, 3
	s_mul_i32 s11, s11, 3
	s_waitcnt vmcnt(0)
	v_readfirstlane_b32 s13, v2
	s_nop 1
	s_add_i32 s13, s13, 1
	s_cmp_lg_u32 s13, s10
	s_cbranch_scc1 .Lnb3_wait
	buffer_wbl2 sc1
	s_waitcnt vmcnt(0)
	v_mov_b32_e32 v1, 0x3400
	global_atomic_add v2, v1, v0, s[0:1] sc0
	s_waitcnt vmcnt(0)
	v_readfirstlane_b32 s13, v2
	s_nop 1
	s_add_i32 s13, s13, 1
	s_cmp_lg_u32 s13, s11
	s_cbranch_scc1 .Lnb3_wait
	v_mov_b32_e32 v1, 0x2400
	global_atomic_add v1, v0, s[0:1]
	global_atomic_add v1, v0, s[0:1] offset:256
	global_atomic_add v1, v0, s[0:1] offset:512
	global_atomic_add v1, v0, s[0:1] offset:768
	global_atomic_add v1, v0, s[0:1] offset:1024
	global_atomic_add v1, v0, s[0:1] offset:1280
	global_atomic_add v1, v0, s[0:1] offset:1536
	global_atomic_add v1, v0, s[0:1] offset:1792
	global_atomic_add v1, v0, s[0:1] offset:2048
	global_atomic_add v1, v0, s[0:1] offset:2304
	global_atomic_add v1, v0, s[0:1] offset:2560
	global_atomic_add v1, v0, s[0:1] offset:2816
	global_atomic_add v1, v0, s[0:1] offset:3072
	global_atomic_add v1, v0, s[0:1] offset:3328
	global_atomic_add v1, v0, s[0:1] offset:3584
	global_atomic_add v1, v0, s[0:1] offset:3840
	v_mov_b32_e32 v1, 0x3500
	global_atomic_add v1, v0, s[0:1]

.Lnb3_spin:
	global_load_dword v2, v1, s[0:1] sc1
	s_waitcnt vmcnt(0)
	v_readfirstlane_b32 s13, v2
	s_nop 1
	s_cmp_ge_u32 s13, 3
	s_cbranch_scc1 .Lnb3_done
	s_sleep 1
	s_add_i32 s15, s15, 1
	s_cmp_lt_u32 s15, 0x200000
	s_cbranch_scc1 .Lnb3_spin

.LBB0_396:
	s_waitcnt vmcnt(0)
	s_waitcnt lgkmcnt(0)
	s_barrier
	s_mov_b64 s[4:5], exec
	v_readlane_b32 s0, v219, 25
	v_readlane_b32 s1, v219, 26
	s_and_b64 s[0:1], s[4:5], s[0:1]
	s_mov_b64 exec, s[0:1]
	s_cbranch_execz .LBB0_448
	v_readlane_b32 s0, v219, 27
	v_readlane_b32 s1, v219, 28
	v_readlane_b32 s2, v219, 29
	v_mov_b32_e32 v0, 0x24000
	s_waitcnt vmcnt(0) lgkmcnt(0)
	ds_read_b32 v2, v0
	ds_read_b32 v0, v0 offset:4
	s_lshl_b32 s3, s2, 8
	s_add_i32 s14, s3, 0x2400
	s_add_i32 s3, s3, 0x1400
	v_mov_b32_e32 v1, s3
	s_waitcnt lgkmcnt(0)
	v_readfirstlane_b32 s10, v2
	v_readfirstlane_b32 s11, v0
	v_mov_b32_e32 v0, 1
	s_nop 1
	global_atomic_add v2, v1, v0, s[0:1] sc0
	s_mul_i32 s10, s10, 4
	s_mul_i32 s11, s11, 4
	s_waitcnt vmcnt(0)
	v_readfirstlane_b32 s13, v2
	s_nop 1
	s_add_i32 s13, s13, 1
	s_cmp_lg_u32 s13, s10
	s_cbranch_scc1 .Lnb4_wait
	buffer_wbl2 sc1
	s_waitcnt vmcnt(0)
	v_mov_b32_e32 v1, 0x3400
	global_atomic_add v2, v1, v0, s[0:1] sc0
	s_waitcnt vmcnt(0)
	v_readfirstlane_b32 s13, v2
	s_nop 1
	s_add_i32 s13, s13, 1
	s_cmp_lg_u32 s13, s11
	s_cbranch_scc1 .Lnb4_wait
	v_mov_b32_e32 v1, 0x2400
	global_atomic_add v1, v0, s[0:1]
	global_atomic_add v1, v0, s[0:1] offset:256
	global_atomic_add v1, v0, s[0:1] offset:512
	global_atomic_add v1, v0, s[0:1] offset:768
	global_atomic_add v1, v0, s[0:1] offset:1024
	global_atomic_add v1, v0, s[0:1] offset:1280
	global_atomic_add v1, v0, s[0:1] offset:1536
	global_atomic_add v1, v0, s[0:1] offset:1792
	global_atomic_add v1, v0, s[0:1] offset:2048
	global_atomic_add v1, v0, s[0:1] offset:2304
	global_atomic_add v1, v0, s[0:1] offset:2560
	global_atomic_add v1, v0, s[0:1] offset:2816
	global_atomic_add v1, v0, s[0:1] offset:3072
	global_atomic_add v1, v0, s[0:1] offset:3328
	global_atomic_add v1, v0, s[0:1] offset:3584
	global_atomic_add v1, v0, s[0:1] offset:3840
	v_mov_b32_e32 v1, 0x3500
	global_atomic_add v1, v0, s[0:1]

.Lnb4_spin:
	global_load_dword v2, v1, s[0:1] sc1
	s_waitcnt vmcnt(0)
	v_readfirstlane_b32 s13, v2
	s_nop 1
	s_cmp_ge_u32 s13, 4
	s_cbranch_scc1 .Lnb4_done
	s_sleep 1
	s_add_i32 s15, s15, 1
	s_cmp_lt_u32 s15, 0x200000
	s_cbranch_scc1 .Lnb4_spin

.LBB0_512:
	s_waitcnt vmcnt(0)
	s_waitcnt vmcnt(0) lgkmcnt(0)
	s_barrier
	s_mov_b64 s[4:5], exec
	v_readlane_b32 s0, v219, 25
	v_readlane_b32 s1, v219, 26
	s_and_b64 s[0:1], s[4:5], s[0:1]
	s_mov_b64 exec, s[0:1]
	s_cbranch_execz .LBB0_564
	v_readlane_b32 s0, v219, 27
	v_readlane_b32 s1, v219, 28
	v_readlane_b32 s2, v219, 29
	v_mov_b32_e32 v0, 0x24000
	s_waitcnt vmcnt(0) lgkmcnt(0)
	ds_read_b32 v2, v0
	ds_read_b32 v0, v0 offset:4
	s_lshl_b32 s3, s2, 8
	s_add_i32 s14, s3, 0x2400
	s_add_i32 s3, s3, 0x1400
	v_mov_b32_e32 v1, s3
	s_waitcnt lgkmcnt(0)
	v_readfirstlane_b32 s10, v2
	v_readfirstlane_b32 s11, v0
	v_mov_b32_e32 v0, 1
	s_nop 1
	global_atomic_add v2, v1, v0, s[0:1] sc0
	s_mul_i32 s10, s10, 5
	s_mul_i32 s11, s11, 5
	s_waitcnt vmcnt(0)
	v_readfirstlane_b32 s13, v2
	s_nop 1
	s_add_i32 s13, s13, 1
	s_cmp_lg_u32 s13, s10
	s_cbranch_scc1 .Lnb5_wait
	buffer_wbl2 sc1
	s_waitcnt vmcnt(0)
	v_mov_b32_e32 v1, 0x3400
	global_atomic_add v2, v1, v0, s[0:1] sc0
	s_waitcnt vmcnt(0)
	v_readfirstlane_b32 s13, v2
	s_nop 1
	s_add_i32 s13, s13, 1
	s_cmp_lg_u32 s13, s11
	s_cbranch_scc1 .Lnb5_wait
	v_mov_b32_e32 v1, 0x2400
	global_atomic_add v1, v0, s[0:1]
	global_atomic_add v1, v0, s[0:1] offset:256
	global_atomic_add v1, v0, s[0:1] offset:512
	global_atomic_add v1, v0, s[0:1] offset:768
	global_atomic_add v1, v0, s[0:1] offset:1024
	global_atomic_add v1, v0, s[0:1] offset:1280
	global_atomic_add v1, v0, s[0:1] offset:1536
	global_atomic_add v1, v0, s[0:1] offset:1792
	global_atomic_add v1, v0, s[0:1] offset:2048
	global_atomic_add v1, v0, s[0:1] offset:2304
	global_atomic_add v1, v0, s[0:1] offset:2560
	global_atomic_add v1, v0, s[0:1] offset:2816
	global_atomic_add v1, v0, s[0:1] offset:3072
	global_atomic_add v1, v0, s[0:1] offset:3328
	global_atomic_add v1, v0, s[0:1] offset:3584
	global_atomic_add v1, v0, s[0:1] offset:3840
	v_mov_b32_e32 v1, 0x3500
	global_atomic_add v1, v0, s[0:1]

.Lnb5_spin:
	global_load_dword v2, v1, s[0:1] sc1
	s_waitcnt vmcnt(0)
	v_readfirstlane_b32 s13, v2
	s_nop 1
	s_cmp_ge_u32 s13, 5
	s_cbranch_scc1 .Lnb5_done
	s_sleep 1
	s_add_i32 s15, s15, 1
	s_cmp_lt_u32 s15, 0x200000
	s_cbranch_scc1 .Lnb5_spin

.LBB0_577:
	s_or_b64 exec, exec, s[4:5]
	s_waitcnt vmcnt(0)
	s_barrier
	s_mov_b64 s[4:5], exec
	v_readlane_b32 s0, v219, 25
	v_readlane_b32 s1, v219, 26
	s_and_b64 s[0:1], s[4:5], s[0:1]
	s_mov_b64 exec, s[0:1]
	s_cbranch_execz .LBB0_629
	v_readlane_b32 s0, v219, 27
	v_readlane_b32 s1, v219, 28
	v_readlane_b32 s2, v219, 29
	v_mov_b32_e32 v0, 0x24000
	s_waitcnt vmcnt(0) lgkmcnt(0)
	ds_read_b32 v2, v0
	ds_read_b32 v0, v0 offset:4
	s_lshl_b32 s3, s2, 8
	s_add_i32 s14, s3, 0x2400
	s_add_i32 s3, s3, 0x1400
	v_mov_b32_e32 v1, s3
	s_waitcnt lgkmcnt(0)
	v_readfirstlane_b32 s10, v2
	v_readfirstlane_b32 s11, v0
	v_mov_b32_e32 v0, 1
	s_nop 1
	global_atomic_add v2, v1, v0, s[0:1] sc0
	s_mul_i32 s10, s10, 6
	s_mul_i32 s11, s11, 6
	s_waitcnt vmcnt(0)
	v_readfirstlane_b32 s13, v2
	s_nop 1
	s_add_i32 s13, s13, 1
	s_cmp_lg_u32 s13, s10
	s_cbranch_scc1 .Lnb6_wait
	buffer_wbl2 sc1
	s_waitcnt vmcnt(0)
	v_mov_b32_e32 v1, 0x3400
	global_atomic_add v2, v1, v0, s[0:1] sc0
	s_waitcnt vmcnt(0)
	v_readfirstlane_b32 s13, v2
	s_nop 1
	s_add_i32 s13, s13, 1
	s_cmp_lg_u32 s13, s11
	s_cbranch_scc1 .Lnb6_wait
	v_mov_b32_e32 v1, 0x2400
	global_atomic_add v1, v0, s[0:1]
	global_atomic_add v1, v0, s[0:1] offset:256
	global_atomic_add v1, v0, s[0:1] offset:512
	global_atomic_add v1, v0, s[0:1] offset:768
	global_atomic_add v1, v0, s[0:1] offset:1024
	global_atomic_add v1, v0, s[0:1] offset:1280
	global_atomic_add v1, v0, s[0:1] offset:1536
	global_atomic_add v1, v0, s[0:1] offset:1792
	global_atomic_add v1, v0, s[0:1] offset:2048
	global_atomic_add v1, v0, s[0:1] offset:2304
	global_atomic_add v1, v0, s[0:1] offset:2560
	global_atomic_add v1, v0, s[0:1] offset:2816
	global_atomic_add v1, v0, s[0:1] offset:3072
	global_atomic_add v1, v0, s[0:1] offset:3328
	global_atomic_add v1, v0, s[0:1] offset:3584
	global_atomic_add v1, v0, s[0:1] offset:3840
	v_mov_b32_e32 v1, 0x3500
	global_atomic_add v1, v0, s[0:1]

.Lnb6_spin:
	global_load_dword v2, v1, s[0:1] sc1
	s_waitcnt vmcnt(0)
	v_readfirstlane_b32 s13, v2
	s_nop 1
	s_cmp_ge_u32 s13, 6
	s_cbranch_scc1 .Lnb6_done
	s_sleep 1
	s_add_i32 s15, s15, 1
	s_cmp_lt_u32 s15, 0x200000
	s_cbranch_scc1 .Lnb6_spin

.Lgu0h_skip:
	s_waitcnt vmcnt(0)
	s_waitcnt vmcnt(0) lgkmcnt(0)
	s_barrier
	s_mov_b64 s[4:5], exec
	v_readlane_b32 s0, v219, 25
	v_readlane_b32 s1, v219, 26
	s_and_b64 s[0:1], s[4:5], s[0:1]
	s_mov_b64 exec, s[0:1]
	s_cbranch_execz .LBB0_745
	v_readlane_b32 s0, v219, 27
	v_readlane_b32 s1, v219, 28
	v_readlane_b32 s2, v219, 29
	v_mov_b32_e32 v0, 0x24000
	s_waitcnt vmcnt(0) lgkmcnt(0)
	ds_read_b32 v2, v0
	ds_read_b32 v0, v0 offset:4
	s_lshl_b32 s3, s2, 8
	s_add_i32 s14, s3, 0x2400
	s_add_i32 s3, s3, 0x1400
	v_mov_b32_e32 v1, s3
	s_waitcnt lgkmcnt(0)
	v_readfirstlane_b32 s10, v2
	v_readfirstlane_b32 s11, v0
	v_mov_b32_e32 v0, 1
	s_nop 1
	global_atomic_add v2, v1, v0, s[0:1] sc0
	s_mul_i32 s10, s10, 7
	s_mul_i32 s11, s11, 7
	s_waitcnt vmcnt(0)
	v_readfirstlane_b32 s13, v2
	s_nop 1
	s_add_i32 s13, s13, 1
	s_cmp_lg_u32 s13, s10
	s_cbranch_scc1 .Lnb7_wait
	buffer_wbl2 sc1
	s_waitcnt vmcnt(0)
	v_mov_b32_e32 v1, 0x3400
	global_atomic_add v2, v1, v0, s[0:1] sc0
	s_waitcnt vmcnt(0)
	v_readfirstlane_b32 s13, v2
	s_nop 1
	s_add_i32 s13, s13, 1
	s_cmp_lg_u32 s13, s11
	s_cbranch_scc1 .Lnb7_wait
	v_mov_b32_e32 v1, 0x2400
	global_atomic_add v1, v0, s[0:1]
	global_atomic_add v1, v0, s[0:1] offset:256
	global_atomic_add v1, v0, s[0:1] offset:512
	global_atomic_add v1, v0, s[0:1] offset:768
	global_atomic_add v1, v0, s[0:1] offset:1024
	global_atomic_add v1, v0, s[0:1] offset:1280
	global_atomic_add v1, v0, s[0:1] offset:1536
	global_atomic_add v1, v0, s[0:1] offset:1792
	global_atomic_add v1, v0, s[0:1] offset:2048
	global_atomic_add v1, v0, s[0:1] offset:2304
	global_atomic_add v1, v0, s[0:1] offset:2560
	global_atomic_add v1, v0, s[0:1] offset:2816
	global_atomic_add v1, v0, s[0:1] offset:3072
	global_atomic_add v1, v0, s[0:1] offset:3328
	global_atomic_add v1, v0, s[0:1] offset:3584
	global_atomic_add v1, v0, s[0:1] offset:3840
	v_mov_b32_e32 v1, 0x3500
	global_atomic_add v1, v0, s[0:1]

.Lnb7_spin:
	global_load_dword v2, v1, s[0:1] sc1
	s_waitcnt vmcnt(0)
	v_readfirstlane_b32 s13, v2
	s_nop 1
	s_cmp_ge_u32 s13, 7
	s_cbranch_scc1 .Lnb7_done
	s_sleep 1
	s_add_i32 s15, s15, 1
	s_cmp_lt_u32 s15, 0x200000
	s_cbranch_scc1 .Lnb7_spin

.LBB0_809:
	s_waitcnt vmcnt(0)
	s_waitcnt vmcnt(0) lgkmcnt(0)
	s_barrier
	s_mov_b64 s[6:7], exec
	v_readlane_b32 s0, v219, 25
	v_readlane_b32 s1, v219, 26
	s_and_b64 s[0:1], s[6:7], s[0:1]
	s_mov_b64 exec, s[0:1]
	s_cbranch_execz .LBB0_861
	v_readlane_b32 s0, v219, 27
	v_readlane_b32 s1, v219, 28
	v_readlane_b32 s2, v219, 29
	v_mov_b32_e32 v0, 0x24000
	s_waitcnt vmcnt(0) lgkmcnt(0)
	ds_read_b32 v2, v0
	ds_read_b32 v0, v0 offset:4
	s_lshl_b32 s3, s2, 8
	s_add_i32 s14, s3, 0x2400
	s_add_i32 s3, s3, 0x1400
	v_mov_b32_e32 v1, s3
	s_waitcnt lgkmcnt(0)
	v_readfirstlane_b32 s10, v2
	v_readfirstlane_b32 s11, v0
	v_mov_b32_e32 v0, 1
	s_nop 1
	global_atomic_add v2, v1, v0, s[0:1] sc0
	s_mul_i32 s10, s10, 8
	s_mul_i32 s11, s11, 8
	s_waitcnt vmcnt(0)
	v_readfirstlane_b32 s13, v2
	s_nop 1
	s_add_i32 s13, s13, 1
	s_cmp_lg_u32 s13, s10
	s_cbranch_scc1 .Lnb8_wait
	buffer_wbl2 sc1
	s_waitcnt vmcnt(0)
	v_mov_b32_e32 v1, 0x3400
	global_atomic_add v2, v1, v0, s[0:1] sc0
	s_waitcnt vmcnt(0)
	v_readfirstlane_b32 s13, v2
	s_nop 1
	s_add_i32 s13, s13, 1
	s_cmp_lg_u32 s13, s11
	s_cbranch_scc1 .Lnb8_wait
	v_mov_b32_e32 v1, 0x2400
	global_atomic_add v1, v0, s[0:1]
	global_atomic_add v1, v0, s[0:1] offset:256
	global_atomic_add v1, v0, s[0:1] offset:512
	global_atomic_add v1, v0, s[0:1] offset:768
	global_atomic_add v1, v0, s[0:1] offset:1024
	global_atomic_add v1, v0, s[0:1] offset:1280
	global_atomic_add v1, v0, s[0:1] offset:1536
	global_atomic_add v1, v0, s[0:1] offset:1792
	global_atomic_add v1, v0, s[0:1] offset:2048
	global_atomic_add v1, v0, s[0:1] offset:2304
	global_atomic_add v1, v0, s[0:1] offset:2560
	global_atomic_add v1, v0, s[0:1] offset:2816
	global_atomic_add v1, v0, s[0:1] offset:3072
	global_atomic_add v1, v0, s[0:1] offset:3328
	global_atomic_add v1, v0, s[0:1] offset:3584
	global_atomic_add v1, v0, s[0:1] offset:3840
	v_mov_b32_e32 v1, 0x3500
	global_atomic_add v1, v0, s[0:1]

.Lnb8_spin:
	global_load_dword v2, v1, s[0:1] sc1
	s_waitcnt vmcnt(0)
	v_readfirstlane_b32 s13, v2
	s_nop 1
	s_cmp_ge_u32 s13, 8
	s_cbranch_scc1 .Lnb8_done
	s_sleep 1
	s_add_i32 s15, s15, 1
	s_cmp_lt_u32 s15, 0x200000
	s_cbranch_scc1 .Lnb8_spin

.LBB0_866:
	s_or_b64 exec, exec, s[6:7]
	s_waitcnt vmcnt(0)
	s_barrier
	s_mov_b64 s[6:7], exec
	v_readlane_b32 s0, v219, 25
	v_readlane_b32 s1, v219, 26
	s_and_b64 s[0:1], s[6:7], s[0:1]
	s_mov_b64 exec, s[0:1]
	s_cbranch_execz .LBB0_918
	v_readlane_b32 s0, v219, 27
	v_readlane_b32 s1, v219, 28
	v_readlane_b32 s2, v219, 29
	v_mov_b32_e32 v0, 0x24000
	s_waitcnt vmcnt(0) lgkmcnt(0)
	ds_read_b32 v2, v0
	ds_read_b32 v0, v0 offset:4
	s_lshl_b32 s3, s2, 8
	s_add_i32 s14, s3, 0x2400
	s_add_i32 s3, s3, 0x1400
	v_mov_b32_e32 v1, s3
	s_waitcnt lgkmcnt(0)
	v_readfirstlane_b32 s10, v2
	v_readfirstlane_b32 s11, v0
	v_mov_b32_e32 v0, 1
	s_nop 1
	global_atomic_add v2, v1, v0, s[0:1] sc0
	s_mul_i32 s10, s10, 9
	s_mul_i32 s11, s11, 9
	s_waitcnt vmcnt(0)
	v_readfirstlane_b32 s13, v2
	s_nop 1
	s_add_i32 s13, s13, 1
	s_cmp_lg_u32 s13, s10
	s_cbranch_scc1 .Lnb9_wait
	buffer_wbl2 sc1
	s_waitcnt vmcnt(0)
	v_mov_b32_e32 v1, 0x3400
	global_atomic_add v2, v1, v0, s[0:1] sc0
	s_waitcnt vmcnt(0)
	v_readfirstlane_b32 s13, v2
	s_nop 1
	s_add_i32 s13, s13, 1
	s_cmp_lg_u32 s13, s11
	s_cbranch_scc1 .Lnb9_wait
	v_mov_b32_e32 v1, 0x2400
	global_atomic_add v1, v0, s[0:1]
	global_atomic_add v1, v0, s[0:1] offset:256
	global_atomic_add v1, v0, s[0:1] offset:512
	global_atomic_add v1, v0, s[0:1] offset:768
	global_atomic_add v1, v0, s[0:1] offset:1024
	global_atomic_add v1, v0, s[0:1] offset:1280
	global_atomic_add v1, v0, s[0:1] offset:1536
	global_atomic_add v1, v0, s[0:1] offset:1792
	global_atomic_add v1, v0, s[0:1] offset:2048
	global_atomic_add v1, v0, s[0:1] offset:2304
	global_atomic_add v1, v0, s[0:1] offset:2560
	global_atomic_add v1, v0, s[0:1] offset:2816
	global_atomic_add v1, v0, s[0:1] offset:3072
	global_atomic_add v1, v0, s[0:1] offset:3328
	global_atomic_add v1, v0, s[0:1] offset:3584
	global_atomic_add v1, v0, s[0:1] offset:3840
	v_mov_b32_e32 v1, 0x3500
	global_atomic_add v1, v0, s[0:1]

.Lnb9_spin:
	global_load_dword v2, v1, s[0:1] sc1
	s_waitcnt vmcnt(0)
	v_readfirstlane_b32 s13, v2
	s_nop 1
	s_cmp_ge_u32 s13, 9
	s_cbranch_scc1 .Lnb9_done
	s_sleep 1
	s_add_i32 s15, s15, 1
	s_cmp_lt_u32 s15, 0x200000
	s_cbranch_scc1 .Lnb9_spin

.LBB0_1035:
	s_waitcnt vmcnt(0)
	s_waitcnt vmcnt(0) lgkmcnt(0)
	s_barrier
	s_mov_b64 s[6:7], exec
	v_readlane_b32 s0, v219, 25
	v_readlane_b32 s1, v219, 26
	s_and_b64 s[0:1], s[6:7], s[0:1]
	s_mov_b64 exec, s[0:1]
	s_cbranch_execz .LBB0_1087
	v_readlane_b32 s0, v219, 27
	v_readlane_b32 s1, v219, 28
	v_readlane_b32 s2, v219, 29
	v_mov_b32_e32 v0, 0x24000
	s_waitcnt vmcnt(0) lgkmcnt(0)
	ds_read_b32 v2, v0
	ds_read_b32 v0, v0 offset:4
	s_lshl_b32 s3, s2, 8
	s_add_i32 s14, s3, 0x2400
	s_add_i32 s3, s3, 0x1400
	v_mov_b32_e32 v1, s3
	s_waitcnt lgkmcnt(0)
	v_readfirstlane_b32 s10, v2
	v_readfirstlane_b32 s11, v0
	v_mov_b32_e32 v0, 1
	s_nop 1
	global_atomic_add v2, v1, v0, s[0:1] sc0
	s_mul_i32 s10, s10, 10
	s_mul_i32 s11, s11, 10
	s_waitcnt vmcnt(0)
	v_readfirstlane_b32 s13, v2
	s_nop 1
	s_add_i32 s13, s13, 1
	s_cmp_lg_u32 s13, s10
	s_cbranch_scc1 .Lnb10_wait
	buffer_wbl2 sc1
	s_waitcnt vmcnt(0)
	v_mov_b32_e32 v1, 0x3400
	global_atomic_add v2, v1, v0, s[0:1] sc0
	s_waitcnt vmcnt(0)
	v_readfirstlane_b32 s13, v2
	s_nop 1
	s_add_i32 s13, s13, 1
	s_cmp_lg_u32 s13, s11
	s_cbranch_scc1 .Lnb10_wait
	v_mov_b32_e32 v1, 0x2400
	global_atomic_add v1, v0, s[0:1]
	global_atomic_add v1, v0, s[0:1] offset:256
	global_atomic_add v1, v0, s[0:1] offset:512
	global_atomic_add v1, v0, s[0:1] offset:768
	global_atomic_add v1, v0, s[0:1] offset:1024
	global_atomic_add v1, v0, s[0:1] offset:1280
	global_atomic_add v1, v0, s[0:1] offset:1536
	global_atomic_add v1, v0, s[0:1] offset:1792
	global_atomic_add v1, v0, s[0:1] offset:2048
	global_atomic_add v1, v0, s[0:1] offset:2304
	global_atomic_add v1, v0, s[0:1] offset:2560
	global_atomic_add v1, v0, s[0:1] offset:2816
	global_atomic_add v1, v0, s[0:1] offset:3072
	global_atomic_add v1, v0, s[0:1] offset:3328
	global_atomic_add v1, v0, s[0:1] offset:3584
	global_atomic_add v1, v0, s[0:1] offset:3840
	v_mov_b32_e32 v1, 0x3500
	global_atomic_add v1, v0, s[0:1]

.Lnb10_spin:
	global_load_dword v2, v1, s[0:1] sc1
	s_waitcnt vmcnt(0)
	v_readfirstlane_b32 s13, v2
	s_nop 1
	s_cmp_ge_u32 s13, 10
	s_cbranch_scc1 .Lnb10_done
	s_sleep 1
	s_add_i32 s15, s15, 1
	s_cmp_lt_u32 s15, 0x200000
	s_cbranch_scc1 .Lnb10_spin

.LBB0_1120:
	s_waitcnt vmcnt(0)
	s_barrier
	s_mov_b64 s[6:7], exec
	v_readlane_b32 s0, v219, 25
	v_readlane_b32 s1, v219, 26
	s_and_b64 s[0:1], s[6:7], s[0:1]
	s_mov_b64 exec, s[0:1]
	s_cbranch_execz .LBB0_1172
	v_readlane_b32 s0, v219, 27
	v_readlane_b32 s1, v219, 28
	v_readlane_b32 s2, v219, 29
	v_mov_b32_e32 v0, 0x24000
	s_waitcnt vmcnt(0) lgkmcnt(0)
	ds_read_b32 v2, v0
	ds_read_b32 v0, v0 offset:4
	s_lshl_b32 s3, s2, 8
	s_add_i32 s14, s3, 0x2400
	s_add_i32 s3, s3, 0x1400
	v_mov_b32_e32 v1, s3
	s_waitcnt lgkmcnt(0)
	v_readfirstlane_b32 s10, v2
	v_readfirstlane_b32 s11, v0
	v_mov_b32_e32 v0, 1
	s_nop 1
	global_atomic_add v2, v1, v0, s[0:1] sc0
	s_mul_i32 s10, s10, 11
	s_mul_i32 s11, s11, 11
	s_waitcnt vmcnt(0)
	v_readfirstlane_b32 s13, v2
	s_nop 1
	s_add_i32 s13, s13, 1
	s_cmp_lg_u32 s13, s10
	s_cbranch_scc1 .Lnb11_wait
	buffer_wbl2 sc1
	s_waitcnt vmcnt(0)
	v_mov_b32_e32 v1, 0x3400
	global_atomic_add v2, v1, v0, s[0:1] sc0
	s_waitcnt vmcnt(0)
	v_readfirstlane_b32 s13, v2
	s_nop 1
	s_add_i32 s13, s13, 1
	s_cmp_lg_u32 s13, s11
	s_cbranch_scc1 .Lnb11_wait
	v_mov_b32_e32 v1, 0x2400
	global_atomic_add v1, v0, s[0:1]
	global_atomic_add v1, v0, s[0:1] offset:256
	global_atomic_add v1, v0, s[0:1] offset:512
	global_atomic_add v1, v0, s[0:1] offset:768
	global_atomic_add v1, v0, s[0:1] offset:1024
	global_atomic_add v1, v0, s[0:1] offset:1280
	global_atomic_add v1, v0, s[0:1] offset:1536
	global_atomic_add v1, v0, s[0:1] offset:1792
	global_atomic_add v1, v0, s[0:1] offset:2048
	global_atomic_add v1, v0, s[0:1] offset:2304
	global_atomic_add v1, v0, s[0:1] offset:2560
	global_atomic_add v1, v0, s[0:1] offset:2816
	global_atomic_add v1, v0, s[0:1] offset:3072
	global_atomic_add v1, v0, s[0:1] offset:3328
	global_atomic_add v1, v0, s[0:1] offset:3584
	global_atomic_add v1, v0, s[0:1] offset:3840
	v_mov_b32_e32 v1, 0x3500
	global_atomic_add v1, v0, s[0:1]

.Lnb11_spin:
	global_load_dword v2, v1, s[0:1] sc1
	s_waitcnt vmcnt(0)
	v_readfirstlane_b32 s13, v2
	s_nop 1
	s_cmp_ge_u32 s13, 11
	s_cbranch_scc1 .Lnb11_done
	s_sleep 1
	s_add_i32 s15, s15, 1
	s_cmp_lt_u32 s15, 0x200000
	s_cbranch_scc1 .Lnb11_spin

.LBB0_1236:
	s_waitcnt vmcnt(0)
	s_waitcnt vmcnt(0) lgkmcnt(0)
	s_barrier
	s_mov_b64 s[6:7], exec
	v_readlane_b32 s0, v219, 25
	v_readlane_b32 s1, v219, 26
	s_and_b64 s[0:1], s[6:7], s[0:1]
	s_mov_b64 exec, s[0:1]
	s_cbranch_execz .LBB0_1288
	v_readlane_b32 s0, v219, 27
	v_readlane_b32 s1, v219, 28
	v_readlane_b32 s2, v219, 29
	v_mov_b32_e32 v0, 0x24000
	s_waitcnt vmcnt(0) lgkmcnt(0)
	ds_read_b32 v2, v0
	ds_read_b32 v0, v0 offset:4
	s_lshl_b32 s3, s2, 8
	s_add_i32 s14, s3, 0x2400
	s_add_i32 s3, s3, 0x1400
	v_mov_b32_e32 v1, s3
	s_waitcnt lgkmcnt(0)
	v_readfirstlane_b32 s10, v2
	v_readfirstlane_b32 s11, v0
	v_mov_b32_e32 v0, 1
	s_nop 1
	global_atomic_add v2, v1, v0, s[0:1] sc0
	s_mul_i32 s10, s10, 12
	s_mul_i32 s11, s11, 12
	s_waitcnt vmcnt(0)
	v_readfirstlane_b32 s13, v2
	s_nop 1
	s_add_i32 s13, s13, 1
	s_cmp_lg_u32 s13, s10
	s_cbranch_scc1 .Lnb12_wait
	buffer_wbl2 sc1
	s_waitcnt vmcnt(0)
	v_mov_b32_e32 v1, 0x3400
	global_atomic_add v2, v1, v0, s[0:1] sc0
	s_waitcnt vmcnt(0)
	v_readfirstlane_b32 s13, v2
	s_nop 1
	s_add_i32 s13, s13, 1
	s_cmp_lg_u32 s13, s11
	s_cbranch_scc1 .Lnb12_wait
	v_mov_b32_e32 v1, 0x2400
	global_atomic_add v1, v0, s[0:1]
	global_atomic_add v1, v0, s[0:1] offset:256
	global_atomic_add v1, v0, s[0:1] offset:512
	global_atomic_add v1, v0, s[0:1] offset:768
	global_atomic_add v1, v0, s[0:1] offset:1024
	global_atomic_add v1, v0, s[0:1] offset:1280
	global_atomic_add v1, v0, s[0:1] offset:1536
	global_atomic_add v1, v0, s[0:1] offset:1792
	global_atomic_add v1, v0, s[0:1] offset:2048
	global_atomic_add v1, v0, s[0:1] offset:2304
	global_atomic_add v1, v0, s[0:1] offset:2560
	global_atomic_add v1, v0, s[0:1] offset:2816
	global_atomic_add v1, v0, s[0:1] offset:3072
	global_atomic_add v1, v0, s[0:1] offset:3328
	global_atomic_add v1, v0, s[0:1] offset:3584
	global_atomic_add v1, v0, s[0:1] offset:3840
	v_mov_b32_e32 v1, 0x3500
	global_atomic_add v1, v0, s[0:1]

.Lnb12_spin:
	global_load_dword v2, v1, s[0:1] sc1
	s_waitcnt vmcnt(0)
	v_readfirstlane_b32 s13, v2
	s_nop 1
	s_cmp_ge_u32 s13, 12
	s_cbranch_scc1 .Lnb12_done
	s_sleep 1
	s_add_i32 s15, s15, 1
	s_cmp_lt_u32 s15, 0x200000
	s_cbranch_scc1 .Lnb12_spin

.LBB0_1293:
	s_or_b64 exec, exec, s[6:7]
	s_waitcnt vmcnt(0)
	s_barrier
	s_mov_b64 s[6:7], exec
	v_readlane_b32 s0, v219, 25
	v_readlane_b32 s1, v219, 26
	s_and_b64 s[0:1], s[6:7], s[0:1]
	s_mov_b64 exec, s[0:1]
	s_cbranch_execz .LBB0_1345
	v_readlane_b32 s0, v219, 27
	v_readlane_b32 s1, v219, 28
	v_readlane_b32 s2, v219, 29
	v_mov_b32_e32 v0, 0x24000
	s_waitcnt vmcnt(0) lgkmcnt(0)
	ds_read_b32 v2, v0
	ds_read_b32 v0, v0 offset:4
	s_lshl_b32 s3, s2, 8
	s_add_i32 s14, s3, 0x2400
	s_add_i32 s3, s3, 0x1400
	v_mov_b32_e32 v1, s3
	s_waitcnt lgkmcnt(0)
	v_readfirstlane_b32 s10, v2
	v_readfirstlane_b32 s11, v0
	v_mov_b32_e32 v0, 1
	s_nop 1
	global_atomic_add v2, v1, v0, s[0:1] sc0
	s_mul_i32 s10, s10, 13
	s_mul_i32 s11, s11, 13
	s_waitcnt vmcnt(0)
	v_readfirstlane_b32 s13, v2
	s_nop 1
	s_add_i32 s13, s13, 1
	s_cmp_lg_u32 s13, s10
	s_cbranch_scc1 .Lnb13_wait
	buffer_wbl2 sc1
	s_waitcnt vmcnt(0)
	v_mov_b32_e32 v1, 0x3400
	global_atomic_add v2, v1, v0, s[0:1] sc0
	s_waitcnt vmcnt(0)
	v_readfirstlane_b32 s13, v2
	s_nop 1
	s_add_i32 s13, s13, 1
	s_cmp_lg_u32 s13, s11
	s_cbranch_scc1 .Lnb13_wait
	v_mov_b32_e32 v1, 0x2400
	global_atomic_add v1, v0, s[0:1]
	global_atomic_add v1, v0, s[0:1] offset:256
	global_atomic_add v1, v0, s[0:1] offset:512
	global_atomic_add v1, v0, s[0:1] offset:768
	global_atomic_add v1, v0, s[0:1] offset:1024
	global_atomic_add v1, v0, s[0:1] offset:1280
	global_atomic_add v1, v0, s[0:1] offset:1536
	global_atomic_add v1, v0, s[0:1] offset:1792
	global_atomic_add v1, v0, s[0:1] offset:2048
	global_atomic_add v1, v0, s[0:1] offset:2304
	global_atomic_add v1, v0, s[0:1] offset:2560
	global_atomic_add v1, v0, s[0:1] offset:2816
	global_atomic_add v1, v0, s[0:1] offset:3072
	global_atomic_add v1, v0, s[0:1] offset:3328
	global_atomic_add v1, v0, s[0:1] offset:3584
	global_atomic_add v1, v0, s[0:1] offset:3840
	v_mov_b32_e32 v1, 0x3500
	global_atomic_add v1, v0, s[0:1]

.Lnb13_spin:
	global_load_dword v2, v1, s[0:1] sc1
	s_waitcnt vmcnt(0)
	v_readfirstlane_b32 s13, v2
	s_nop 1
	s_cmp_ge_u32 s13, 13
	s_cbranch_scc1 .Lnb13_done
	s_sleep 1
	s_add_i32 s15, s15, 1
	s_cmp_lt_u32 s15, 0x200000
	s_cbranch_scc1 .Lnb13_spin

.LBB0_1409:
	s_waitcnt vmcnt(0)
	s_waitcnt vmcnt(0) lgkmcnt(0)
	s_barrier
	s_mov_b64 s[6:7], exec
	v_readlane_b32 s0, v219, 25
	v_readlane_b32 s1, v219, 26
	s_and_b64 s[0:1], s[6:7], s[0:1]
	s_mov_b64 exec, s[0:1]
	s_cbranch_execz .LBB0_1461
	v_readlane_b32 s0, v219, 27
	v_readlane_b32 s1, v219, 28
	v_readlane_b32 s2, v219, 29
	v_mov_b32_e32 v0, 0x24000
	s_waitcnt vmcnt(0) lgkmcnt(0)
	ds_read_b32 v2, v0
	ds_read_b32 v0, v0 offset:4
	s_lshl_b32 s3, s2, 8
	s_add_i32 s14, s3, 0x2400
	s_add_i32 s3, s3, 0x1400
	v_mov_b32_e32 v1, s3
	s_waitcnt lgkmcnt(0)
	v_readfirstlane_b32 s10, v2
	v_readfirstlane_b32 s11, v0
	v_mov_b32_e32 v0, 1
	s_nop 1
	global_atomic_add v2, v1, v0, s[0:1] sc0
	s_mul_i32 s10, s10, 14
	s_mul_i32 s11, s11, 14
	s_waitcnt vmcnt(0)
	v_readfirstlane_b32 s13, v2
	s_nop 1
	s_add_i32 s13, s13, 1
	s_cmp_lg_u32 s13, s10
	s_cbranch_scc1 .Lnb14_wait
	buffer_wbl2 sc1
	s_waitcnt vmcnt(0)
	v_mov_b32_e32 v1, 0x3400
	global_atomic_add v2, v1, v0, s[0:1] sc0
	s_waitcnt vmcnt(0)
	v_readfirstlane_b32 s13, v2
	s_nop 1
	s_add_i32 s13, s13, 1
	s_cmp_lg_u32 s13, s11
	s_cbranch_scc1 .Lnb14_wait
	v_mov_b32_e32 v1, 0x2400
	global_atomic_add v1, v0, s[0:1]
	global_atomic_add v1, v0, s[0:1] offset:256
	global_atomic_add v1, v0, s[0:1] offset:512
	global_atomic_add v1, v0, s[0:1] offset:768
	global_atomic_add v1, v0, s[0:1] offset:1024
	global_atomic_add v1, v0, s[0:1] offset:1280
	global_atomic_add v1, v0, s[0:1] offset:1536
	global_atomic_add v1, v0, s[0:1] offset:1792
	global_atomic_add v1, v0, s[0:1] offset:2048
	global_atomic_add v1, v0, s[0:1] offset:2304
	global_atomic_add v1, v0, s[0:1] offset:2560
	global_atomic_add v1, v0, s[0:1] offset:2816
	global_atomic_add v1, v0, s[0:1] offset:3072
	global_atomic_add v1, v0, s[0:1] offset:3328
	global_atomic_add v1, v0, s[0:1] offset:3584
	global_atomic_add v1, v0, s[0:1] offset:3840
	v_mov_b32_e32 v1, 0x3500
	global_atomic_add v1, v0, s[0:1]

.Lnb14_spin:
	global_load_dword v2, v1, s[0:1] sc1
	s_waitcnt vmcnt(0)
	v_readfirstlane_b32 s13, v2
	s_nop 1
	s_cmp_ge_u32 s13, 14
	s_cbranch_scc1 .Lnb14_done
	s_sleep 1
	s_add_i32 s15, s15, 1
	s_cmp_lt_u32 s15, 0x200000
	s_cbranch_scc1 .Lnb14_spin

.LBB0_1525:
	s_waitcnt vmcnt(0)
	s_waitcnt vmcnt(0) lgkmcnt(0)
	s_barrier
	s_mov_b64 s[4:5], exec
	v_readlane_b32 s0, v219, 25
	v_readlane_b32 s1, v219, 26
	s_and_b64 s[0:1], s[4:5], s[0:1]
	s_mov_b64 exec, s[0:1]
	s_cbranch_execz .LBB0_1577
	v_readlane_b32 s0, v219, 27
	v_readlane_b32 s1, v219, 28
	v_readlane_b32 s2, v219, 29
	v_mov_b32_e32 v0, 0x24000
	s_waitcnt vmcnt(0) lgkmcnt(0)
	ds_read_b32 v2, v0
	ds_read_b32 v0, v0 offset:4
	s_lshl_b32 s3, s2, 8
	s_add_i32 s14, s3, 0x2400
	s_add_i32 s3, s3, 0x1400
	v_mov_b32_e32 v1, s3
	s_waitcnt lgkmcnt(0)
	v_readfirstlane_b32 s10, v2
	v_readfirstlane_b32 s11, v0
	v_mov_b32_e32 v0, 1
	s_nop 1
	global_atomic_add v2, v1, v0, s[0:1] sc0
	s_mul_i32 s10, s10, 15
	s_mul_i32 s11, s11, 15
	s_waitcnt vmcnt(0)
	v_readfirstlane_b32 s13, v2
	s_nop 1
	s_add_i32 s13, s13, 1
	s_cmp_lg_u32 s13, s10
	s_cbranch_scc1 .Lnb15_wait
	buffer_wbl2 sc1
	s_waitcnt vmcnt(0)
	v_mov_b32_e32 v1, 0x3400
	global_atomic_add v2, v1, v0, s[0:1] sc0
	s_waitcnt vmcnt(0)
	v_readfirstlane_b32 s13, v2
	s_nop 1
	s_add_i32 s13, s13, 1
	s_cmp_lg_u32 s13, s11
	s_cbranch_scc1 .Lnb15_wait
	v_mov_b32_e32 v1, 0x2400
	global_atomic_add v1, v0, s[0:1]
	global_atomic_add v1, v0, s[0:1] offset:256
	global_atomic_add v1, v0, s[0:1] offset:512
	global_atomic_add v1, v0, s[0:1] offset:768
	global_atomic_add v1, v0, s[0:1] offset:1024
	global_atomic_add v1, v0, s[0:1] offset:1280
	global_atomic_add v1, v0, s[0:1] offset:1536
	global_atomic_add v1, v0, s[0:1] offset:1792
	global_atomic_add v1, v0, s[0:1] offset:2048
	global_atomic_add v1, v0, s[0:1] offset:2304
	global_atomic_add v1, v0, s[0:1] offset:2560
	global_atomic_add v1, v0, s[0:1] offset:2816
	global_atomic_add v1, v0, s[0:1] offset:3072
	global_atomic_add v1, v0, s[0:1] offset:3328
	global_atomic_add v1, v0, s[0:1] offset:3584
	global_atomic_add v1, v0, s[0:1] offset:3840
	v_mov_b32_e32 v1, 0x3500
	global_atomic_add v1, v0, s[0:1]

.Lnb15_spin:
	global_load_dword v2, v1, s[0:1] sc1
	s_waitcnt vmcnt(0)
	v_readfirstlane_b32 s13, v2
	s_nop 1
	s_cmp_ge_u32 s13, 15
	s_cbranch_scc1 .Lnb15_done
	s_sleep 1
	s_add_i32 s15, s15, 1
	s_cmp_lt_u32 s15, 0x200000
	s_cbranch_scc1 .Lnb15_spin
